# MLA sample loop: softmax row-max via v_permlane16/32_swap instead of ds_bpermute; K/V tile prefetch addresses via scalar bases; per-XCD queues
# speedup vs baseline: 1.0111x; 1.0111x over previous
.LBB0_1438:
	s_cmpk_lt_u32 s10, 0x46
	s_cselect_b64 s[44:45], -1, 0
	s_cmpk_gt_u32 s10, 0x45
	s_cselect_b64 s[42:43], -1, 0
	s_and_b64 vcc, exec, s[42:43]
	s_cbranch_vccnz .LBB0_1440
	s_lshl_b64 s[50:51], s[40:41], 11
	s_add_u32 s50, s50, s20
	s_addc_u32 s51, s51, s21
	s_add_u32 s50, s50, s2
	s_addc_u32 s51, s51, -1
	v_lshrrev_b32_e32 v226, 4, v179
	v_and_b32_e32 v228, 15, v179
	v_lshlrev_b32_e32 v226, 11, v226
	v_lshl_or_b32 v226, v228, 4, v226
	s_add_u32 s52, s50, 0x8000
	s_addc_u32 s53, s51, 0
	s_add_u32 s54, s50, 0x10000
	s_addc_u32 s55, s51, 0
	s_add_u32 s56, s50, 0x18000
	s_addc_u32 s57, s51, 0
	global_load_dwordx4 v[36:39], v226, s[50:51]
	global_load_dwordx4 v[40:43], v226, s[52:53]
	global_load_dwordx4 v[44:47], v226, s[54:55]
	global_load_dwordx4 v[48:51], v226, s[56:57]
	v_lshrrev_b32_e32 v227, 3, v179
	v_and_b32_e32 v228, 7, v179
	v_lshlrev_b32_e32 v228, 4, v228
	v_mad_u32_u24 v227, v227, s15, v228
	s_lshl_b32 s5, s15, 5
	s_add_u32 s58, s34, s5
	s_addc_u32 s59, s35, 0
	global_load_dwordx4 v[60:63], v227, s[34:35] offset:-128
	global_load_dwordx4 v[64:67], v227, s[58:59] offset:-128
.LBB0_1440:
	ds_read_b128 v[116:119], v155
	ds_read_b128 v[120:123], v155 offset:64
	ds_read_b128 v[124:127], v155 offset:128
	ds_read_b128 v[128:131], v155 offset:192
	ds_read_b128 v[132:135], v155 offset:4352
	ds_read_b128 v[136:139], v155 offset:4416
	ds_read_b128 v[140:143], v155 offset:4480
	ds_read_b128 v[144:147], v155 offset:4544
	ds_read_b128 v[172:175], v155 offset:8704
	ds_read_b128 v[180:183], v155 offset:8768
	ds_read_b128 v[184:187], v155 offset:8832
	ds_read_b128 v[188:191], v155 offset:8896
	ds_read_b128 v[192:195], v155 offset:13056
	ds_read_b128 v[196:199], v155 offset:13120
	ds_read_b128 v[200:203], v155 offset:13184
	ds_read_b128 v[204:207], v155 offset:13248
	s_waitcnt lgkmcnt(14)
	v_mfma_f32_16x16x32_bf16 v[216:219], v[116:119], v[4:7], 0
	v_and_b32_e32 v2, 64, v215
	v_xor_b32_e32 v0, 16, v215
	v_add_u32_e32 v2, 64, v2
	v_mfma_f32_16x16x32_bf16 v[116:119], v[116:119], v[20:23], 0
	v_cmp_lt_i32_e32 vcc, v0, v2
	v_mfma_f32_16x16x32_bf16 v[216:219], v[120:123], v[8:11], v[216:219]
	s_nop 0
	v_cndmask_b32_e32 v0, v215, v0, vcc
	v_lshlrev_b32_e32 v169, 2, v0
	v_xor_b32_e32 v0, 32, v215
	v_mfma_f32_16x16x32_bf16 v[116:119], v[120:123], v[24:27], v[116:119]
	v_cmp_lt_i32_e32 vcc, v0, v2
	s_waitcnt lgkmcnt(13)
	v_mfma_f32_16x16x32_bf16 v[120:123], v[124:127], v[12:15], v[216:219]
	v_cndmask_b32_e32 v0, v215, v0, vcc
	v_lshlrev_b32_e32 v168, 2, v0
	v_mfma_f32_16x16x32_bf16 v[116:119], v[124:127], v[28:31], v[116:119]
	s_waitcnt lgkmcnt(12)
	v_mfma_f32_16x16x32_bf16 v[216:219], v[128:131], v[16:19], v[120:123]
	v_mfma_f32_16x16x32_bf16 v[120:123], v[128:131], v[32:35], v[116:119]
	s_waitcnt lgkmcnt(11)
	v_mfma_f32_16x16x32_bf16 v[116:119], v[132:135], v[4:7], 0
	s_nop 4
	v_mul_f32_e32 v0, 0x3e0293ee, v216
	v_mul_f32_e32 v2, 0x3e0293ee, v217
	v_max3_f32 v0, v0, s82, v2
	v_mfma_f32_16x16x32_bf16 v[124:127], v[132:135], v[20:23], 0
	v_mul_f32_e32 v2, 0x3e0293ee, v218
	v_mul_f32_e32 v3, 0x3e0293ee, v219
	v_max3_f32 v0, v0, v2, v3
	s_waitcnt lgkmcnt(10)
	v_mfma_f32_16x16x32_bf16 v[116:119], v[136:139], v[8:11], v[116:119]
	v_mfma_f32_16x16x32_bf16 v[124:127], v[136:139], v[24:27], v[124:127]
	s_waitcnt lgkmcnt(9)
	v_mfma_f32_16x16x32_bf16 v[116:119], v[140:143], v[12:15], v[116:119]
	v_mfma_f32_16x16x32_bf16 v[124:127], v[140:143], v[28:31], v[124:127]
	s_waitcnt lgkmcnt(8)
	v_mfma_f32_16x16x32_bf16 v[140:143], v[144:147], v[16:19], v[116:119]
	s_waitcnt lgkmcnt(7)
	v_mfma_f32_16x16x32_bf16 v[116:119], v[172:175], v[4:7], 0
	s_waitcnt lgkmcnt(6)
	v_mfma_f32_16x16x32_bf16 v[116:119], v[180:183], v[8:11], v[116:119]
	s_nop 3
	v_mul_f32_e32 v2, 0x3e0293ee, v140
	v_mul_f32_e32 v3, 0x3e0293ee, v141
	v_max3_f32 v0, v0, v2, v3
	s_waitcnt lgkmcnt(5)
	v_mfma_f32_16x16x32_bf16 v[116:119], v[184:187], v[12:15], v[116:119]
	v_mul_f32_e32 v2, 0x3e0293ee, v142
	v_mul_f32_e32 v3, 0x3e0293ee, v143
	v_max3_f32 v0, v0, v2, v3
	s_waitcnt lgkmcnt(4)
	v_mfma_f32_16x16x32_bf16 v[136:139], v[188:191], v[16:19], v[116:119]
	s_waitcnt lgkmcnt(3)
	v_mfma_f32_16x16x32_bf16 v[116:119], v[192:195], v[4:7], 0
	v_mfma_f32_16x16x32_bf16 v[132:135], v[192:195], v[20:23], 0
	s_nop 4
	v_mul_f32_e32 v2, 0x3e0293ee, v136
	v_mul_f32_e32 v3, 0x3e0293ee, v137
	v_max3_f32 v0, v0, v2, v3
	s_waitcnt lgkmcnt(2)
	v_mfma_f32_16x16x32_bf16 v[116:119], v[196:199], v[8:11], v[116:119]
	v_mul_f32_e32 v2, 0x3e0293ee, v138
	v_mul_f32_e32 v3, 0x3e0293ee, v139
	v_max3_f32 v0, v0, v2, v3
	v_mfma_f32_16x16x32_bf16 v[132:135], v[196:199], v[24:27], v[132:135]
	s_waitcnt lgkmcnt(1)
	v_mfma_f32_16x16x32_bf16 v[116:119], v[200:203], v[12:15], v[116:119]
	v_mfma_f32_16x16x32_bf16 v[128:131], v[144:147], v[32:35], v[124:127]
	v_mfma_f32_16x16x32_bf16 v[144:147], v[200:203], v[28:31], v[132:135]
	s_waitcnt lgkmcnt(0)
	v_mfma_f32_16x16x32_bf16 v[132:135], v[204:207], v[16:19], v[116:119]
	v_mfma_f32_16x16x32_bf16 v[124:127], v[172:175], v[20:23], 0
	v_mfma_f32_16x16x32_bf16 v[124:127], v[180:183], v[24:27], v[124:127]
	s_nop 5
	v_mul_f32_e32 v2, 0x3e0293ee, v132
	v_mul_f32_e32 v3, 0x3e0293ee, v133
	v_max3_f32 v0, v0, v2, v3
	v_mul_f32_e32 v2, 0x3e0293ee, v134
	v_mul_f32_e32 v3, 0x3e0293ee, v135
	v_max3_f32 v0, v0, v2, v3
	v_mov_b32_e32 v2, v0
	v_mfma_f32_16x16x32_bf16 v[124:127], v[184:187], v[28:31], v[124:127]
	s_waitcnt lgkmcnt(0)
	s_nop 1
	v_permlane16_swap_b32_e32 v2, v0
	v_max_f32_e32 v0, v0, v2
	v_mov_b32_e32 v2, v0
	v_mfma_f32_16x16x32_bf16 v[124:127], v[188:191], v[32:35], v[124:127]
	s_waitcnt lgkmcnt(0)
	s_nop 1
	v_permlane32_swap_b32_e32 v2, v0
	v_max3_f32 v0, v170, v0, v2
	v_fma_f32 v2, v216, s74, -v0
	v_exp_f32_e32 v173, v2
	v_fma_f32 v3, v217, s74, -v0
	v_exp_f32_e32 v174, v3
	v_fma_f32 v3, v218, s74, -v0
	v_exp_f32_e32 v175, v3
	v_fma_f32 v3, v219, s74, -v0
	v_exp_f32_e32 v176, v3
	v_fma_f32 v3, v140, s74, -v0
	v_add_f32_e32 v2, 0, v173
	v_exp_f32_e32 v177, v3
	v_fma_f32 v3, v141, s74, -v0
	v_add_f32_e32 v2, v174, v2
	v_exp_f32_e32 v180, v3
	v_fma_f32 v3, v142, s74, -v0
	v_add_f32_e32 v2, v175, v2
	v_exp_f32_e32 v181, v3
	v_fma_f32 v3, v143, s74, -v0
	v_add_f32_e32 v2, v176, v2
	v_exp_f32_e32 v183, v3
	v_fma_f32 v3, v136, s74, -v0
	v_add_f32_e32 v2, v177, v2
	v_exp_f32_e32 v182, v3
	v_fma_f32 v3, v137, s74, -v0
	v_add_f32_e32 v2, v180, v2
	v_exp_f32_e32 v184, v3
	v_fma_f32 v3, v138, s74, -v0
	v_add_f32_e32 v2, v181, v2
	v_exp_f32_e32 v185, v3
	v_fma_f32 v3, v139, s74, -v0
	v_add_f32_e32 v2, v183, v2
	v_exp_f32_e32 v186, v3
	v_fma_f32 v3, v132, s74, -v0
	v_add_f32_e32 v2, v182, v2
	v_exp_f32_e32 v187, v3
	v_fma_f32 v3, v133, s74, -v0
	v_add_f32_e32 v2, v184, v2
	v_exp_f32_e32 v188, v3
	v_fma_f32 v3, v134, s74, -v0
	v_add_f32_e32 v2, v185, v2
	v_exp_f32_e32 v189, v3
	v_fma_f32 v3, v135, s74, -v0
	v_add_f32_e32 v2, v186, v2
	v_exp_f32_e32 v190, v3
	v_mfma_f32_16x16x32_bf16 v[116:119], v[204:207], v[32:35], v[144:147]
	v_add_f32_e32 v2, v187, v2
	v_add_f32_e32 v2, v188, v2
	v_add_f32_e32 v2, v189, v2
	v_cmp_gt_f32_e32 vcc, v0, v170
	v_add_f32_e32 v2, v190, v2
	s_cbranch_vccz .LBB0_1456
	v_sub_f32_e32 v3, v170, v0
	v_exp_f32_e32 v144, v3
	v_mov_b32_e32 v159, v157
	v_fma_f32 v158, v156, v144, v2
	v_pk_mul_f32 v[134:135], v[114:115], v[144:145] op_sel_hi:[1,0]
	v_pk_mul_f32 v[132:133], v[112:113], v[144:145] op_sel_hi:[1,0]
	v_pk_mul_f32 v[138:139], v[110:111], v[144:145] op_sel_hi:[1,0]
	v_pk_mul_f32 v[136:137], v[108:109], v[144:145] op_sel_hi:[1,0]
	v_pk_mul_f32 v[142:143], v[106:107], v[144:145] op_sel_hi:[1,0]
	v_pk_mul_f32 v[140:141], v[104:105], v[144:145] op_sel_hi:[1,0]
	v_pk_mul_f32 v[146:147], v[102:103], v[144:145] op_sel_hi:[1,0]
	v_pk_mul_f32 v[144:145], v[100:101], v[144:145] op_sel_hi:[1,0]
	s_cbranch_execnz .LBB0_1443

.LBB0_1443:
	v_mul_f32_e32 v2, 0x3e0293ee, v120
	v_mul_f32_e32 v3, 0x3e0293ee, v121
	v_max3_f32 v2, v2, s82, v3
	v_mul_f32_e32 v3, 0x3e0293ee, v122
	v_mul_f32_e32 v100, 0x3e0293ee, v123
	v_max3_f32 v2, v2, v3, v100
	v_mul_f32_e32 v3, 0x3e0293ee, v128
	v_mul_f32_e32 v100, 0x3e0293ee, v129
	v_max3_f32 v2, v2, v3, v100
	v_mul_f32_e32 v3, 0x3e0293ee, v130
	v_mul_f32_e32 v100, 0x3e0293ee, v131
	v_max3_f32 v2, v2, v3, v100
	v_mul_f32_e32 v3, 0x3e0293ee, v124
	v_mul_f32_e32 v100, 0x3e0293ee, v125
	v_max3_f32 v2, v2, v3, v100
	v_mul_f32_e32 v3, 0x3e0293ee, v126
	v_mul_f32_e32 v100, 0x3e0293ee, v127
	v_max3_f32 v2, v2, v3, v100
	v_mul_f32_e32 v3, 0x3e0293ee, v116
	v_mul_f32_e32 v100, 0x3e0293ee, v117
	v_max3_f32 v2, v2, v3, v100
	v_mul_f32_e32 v3, 0x3e0293ee, v118
	v_mul_f32_e32 v100, 0x3e0293ee, v119
	v_max3_f32 v2, v2, v3, v100
	v_mov_b32_e32 v3, v2
	s_waitcnt lgkmcnt(0)
	s_nop 1
	v_permlane16_swap_b32_e32 v3, v2
	v_max_f32_e32 v2, v2, v3
	v_mov_b32_e32 v3, v2
	s_waitcnt lgkmcnt(0)
	s_nop 1
	v_permlane32_swap_b32_e32 v3, v2
	v_max3_f32 v172, v171, v2, v3
	v_fma_f32 v2, v120, s74, -v172
	v_exp_f32_e32 v120, v2
	v_fma_f32 v2, v121, s74, -v172
	v_exp_f32_e32 v121, v2
	v_fma_f32 v2, v122, s74, -v172
	v_exp_f32_e32 v122, v2
	v_fma_f32 v2, v123, s74, -v172
	v_exp_f32_e32 v123, v2
	v_fma_f32 v3, v128, s74, -v172
	v_add_f32_e32 v2, 0, v120
	v_exp_f32_e32 v128, v3
	v_fma_f32 v3, v129, s74, -v172
	v_add_f32_e32 v2, v121, v2
	v_exp_f32_e32 v129, v3
	v_fma_f32 v3, v130, s74, -v172
	v_add_f32_e32 v2, v122, v2
	v_exp_f32_e32 v130, v3
	v_fma_f32 v3, v131, s74, -v172
	v_add_f32_e32 v2, v123, v2
	v_exp_f32_e32 v131, v3
	v_fma_f32 v3, v124, s74, -v172
	v_add_f32_e32 v2, v128, v2
	v_exp_f32_e32 v124, v3
	v_fma_f32 v3, v125, s74, -v172
	v_add_f32_e32 v2, v129, v2
	v_exp_f32_e32 v125, v3
	v_fma_f32 v3, v126, s74, -v172
	v_add_f32_e32 v2, v130, v2
	v_exp_f32_e32 v126, v3
	v_fma_f32 v3, v127, s74, -v172
	v_add_f32_e32 v2, v131, v2
	v_exp_f32_e32 v127, v3
	v_fma_f32 v3, v116, s74, -v172
	v_add_f32_e32 v2, v124, v2
	v_exp_f32_e32 v116, v3
	v_fma_f32 v3, v117, s74, -v172
	v_add_f32_e32 v2, v125, v2
	v_exp_f32_e32 v117, v3
	v_fma_f32 v3, v118, s74, -v172
	v_add_f32_e32 v2, v126, v2
	v_exp_f32_e32 v118, v3
	v_fma_f32 v3, v119, s74, -v172
	v_add_f32_e32 v2, v127, v2
	v_exp_f32_e32 v119, v3
	v_add_f32_e32 v2, v116, v2
	v_add_f32_e32 v2, v117, v2
	v_add_f32_e32 v2, v118, v2
	v_cmp_gt_f32_e32 vcc, v172, v171
	v_add_f32_e32 v156, v119, v2
	s_cbranch_vccz .LBB0_1457
	v_sub_f32_e32 v2, v171, v172
	v_exp_f32_e32 v112, v2
	v_mov_b32_e32 v2, v158
	v_fma_f32 v3, v159, v112, v156
	v_pk_mul_f32 v[102:103], v[98:99], v[112:113] op_sel_hi:[1,0]
	v_pk_mul_f32 v[100:101], v[96:97], v[112:113] op_sel_hi:[1,0]
	v_pk_mul_f32 v[106:107], v[94:95], v[112:113] op_sel_hi:[1,0]
	v_pk_mul_f32 v[104:105], v[92:93], v[112:113] op_sel_hi:[1,0]
	v_pk_mul_f32 v[110:111], v[90:91], v[112:113] op_sel_hi:[1,0]
	v_pk_mul_f32 v[108:109], v[88:89], v[112:113] op_sel_hi:[1,0]
	v_pk_mul_f32 v[114:115], v[86:87], v[112:113] op_sel_hi:[1,0]
	v_pk_mul_f32 v[112:113], v[84:85], v[112:113] op_sel_hi:[1,0]
	s_cbranch_execnz .LBB0_1446

.LBB0_1446:
	v_add_u32_e32 v156, 0x4000, v164
	v_add_u32_e32 v170, 0x4000, v165
	v_add_u32_e32 v171, 0x4000, v166
	v_add_u32_e32 v191, 0x4000, v167
	ds_read2_b64 v[84:87], v156 offset0:128 offset1:132
	ds_read2_b64 v[88:91], v170 offset0:128 offset1:132
	ds_read2_b64 v[92:95], v171 offset0:128 offset1:132
	ds_read2_b64 v[96:99], v191 offset0:128 offset1:132
	ds_read2_b64 v[156:159], v156 offset0:136 offset1:140
	ds_read2_b64 v[192:195], v170 offset0:136 offset1:140
	ds_read2_b64 v[196:199], v171 offset0:136 offset1:140
	ds_read2_b64 v[200:203], v191 offset0:136 offset1:140
	v_cvt_pk_bf16_f32 v174, v173, v174
	v_cvt_pk_bf16_f32 v175, v175, v176
	v_cvt_pk_bf16_f32 v176, v177, v180
	v_cvt_pk_bf16_f32 v177, v181, v183
	v_cvt_pk_bf16_f32 v120, v120, v121
	v_cvt_pk_bf16_f32 v121, v122, v123
	v_cvt_pk_bf16_f32 v122, v128, v129
	v_cvt_pk_bf16_f32 v123, v130, v131
	v_cvt_pk_bf16_f32 v128, v182, v184
	v_cvt_pk_bf16_f32 v129, v185, v186
	v_cvt_pk_bf16_f32 v130, v187, v188
	v_cvt_pk_bf16_f32 v131, v189, v190
	v_cvt_pk_bf16_f32 v124, v124, v125
	v_cvt_pk_bf16_f32 v125, v126, v127
	v_cvt_pk_bf16_f32 v126, v116, v117
	v_cvt_pk_bf16_f32 v127, v118, v119
	s_waitcnt lgkmcnt(7)
	v_mfma_f32_16x16x32_bf16 v[116:119], v[84:87], v[174:177], v[132:135]
	s_cmpk_gt_u32 s10, 0x44
	s_waitcnt vmcnt(5)
	ds_write_b128 v160, v[52:55] offset:26624
	s_waitcnt vmcnt(4)
	ds_write_b128 v161, v[56:59] offset:26624
	s_waitcnt vmcnt(3)
	ds_write_b128 v162, v[68:71] offset:26624
	s_waitcnt vmcnt(2)
	ds_write_b128 v163, v[72:75] offset:26624
	s_waitcnt vmcnt(1)
	ds_write_b128 v152, v[76:79] offset:44032
	s_waitcnt vmcnt(0)
	ds_write_b128 v154, v[80:83] offset:44032
	v_mfma_f32_16x16x32_bf16 v[84:87], v[84:87], v[120:123], v[100:103]
	s_waitcnt lgkmcnt(0)
	s_barrier
	v_mfma_f32_16x16x32_bf16 v[132:135], v[88:91], v[174:177], v[136:139]
	v_mfma_f32_16x16x32_bf16 v[88:91], v[88:91], v[120:123], v[104:107]
	v_mfma_f32_16x16x32_bf16 v[136:139], v[92:95], v[174:177], v[140:143]
	v_mfma_f32_16x16x32_bf16 v[92:95], v[92:95], v[120:123], v[108:111]
	v_mfma_f32_16x16x32_bf16 v[140:143], v[96:99], v[174:177], v[144:147]
	v_mfma_f32_16x16x32_bf16 v[96:99], v[96:99], v[120:123], v[112:115]
	v_mfma_f32_16x16x32_bf16 v[100:103], v[156:159], v[128:131], v[116:119]
	v_mfma_f32_16x16x32_bf16 v[84:87], v[156:159], v[124:127], v[84:87]
	v_mfma_f32_16x16x32_bf16 v[104:107], v[192:195], v[128:131], v[132:135]
	v_mfma_f32_16x16x32_bf16 v[88:91], v[192:195], v[124:127], v[88:91]
	v_mfma_f32_16x16x32_bf16 v[108:111], v[196:199], v[128:131], v[136:139]
	v_mfma_f32_16x16x32_bf16 v[92:95], v[196:199], v[124:127], v[92:95]
	v_mfma_f32_16x16x32_bf16 v[112:115], v[200:203], v[128:131], v[140:143]
	v_mfma_f32_16x16x32_bf16 v[96:99], v[200:203], v[124:127], v[96:99]
	s_cbranch_scc1 .LBB0_1448
	s_lshl_b64 s[50:51], s[40:41], 11
	s_add_u32 s50, s50, s20
	s_addc_u32 s51, s51, s21
	v_lshrrev_b32_e32 v226, 4, v179
	v_and_b32_e32 v228, 15, v179
	v_lshlrev_b32_e32 v226, 11, v226
	v_lshl_or_b32 v226, v228, 4, v226
	s_add_u32 s52, s50, 0x8000
	s_addc_u32 s53, s51, 0
	s_add_u32 s54, s50, 0x10000
	s_addc_u32 s55, s51, 0
	s_add_u32 s56, s50, 0x18000
	s_addc_u32 s57, s51, 0
	global_load_dwordx4 v[52:55], v226, s[50:51]
	global_load_dwordx4 v[56:59], v226, s[52:53]
	global_load_dwordx4 v[68:71], v226, s[54:55]
	global_load_dwordx4 v[72:75], v226, s[56:57]
	v_lshrrev_b32_e32 v227, 3, v179
	v_and_b32_e32 v228, 7, v179
	v_lshlrev_b32_e32 v228, 4, v228
	v_mad_u32_u24 v227, v227, s15, v228
	s_lshl_b32 s5, s15, 5
	s_add_u32 s58, s34, s5
	s_addc_u32 s59, s35, 0
	global_load_dwordx4 v[76:79], v227, s[34:35]
	global_load_dwordx4 v[80:83], v227, s[58:59]
.LBB0_1448:
	ds_read_b128 v[116:119], v155 offset:26624
	ds_read_b128 v[120:123], v155 offset:26688
	ds_read_b128 v[124:127], v155 offset:26752
	ds_read_b128 v[128:131], v155 offset:26816
	ds_read_b128 v[132:135], v155 offset:30976
	ds_read_b128 v[136:139], v155 offset:31040
	ds_read_b128 v[140:143], v155 offset:31104
	ds_read_b128 v[144:147], v155 offset:31168
	ds_read_b128 v[156:159], v155 offset:35328
	ds_read_b128 v[174:177], v155 offset:35392
	ds_read_b128 v[180:183], v155 offset:35456
	ds_read_b128 v[184:187], v155 offset:35520
	ds_read_b128 v[188:191], v155 offset:39680
	ds_read_b128 v[192:195], v155 offset:39744
	ds_read_b128 v[196:199], v155 offset:39808
	ds_read_b128 v[200:203], v155 offset:39872
	s_waitcnt lgkmcnt(14)
	v_mfma_f32_16x16x32_bf16 v[204:207], v[116:119], v[4:7], 0
	v_mfma_f32_16x16x32_bf16 v[116:119], v[116:119], v[20:23], 0
	v_mfma_f32_16x16x32_bf16 v[204:207], v[120:123], v[8:11], v[204:207]
	v_mfma_f32_16x16x32_bf16 v[116:119], v[120:123], v[24:27], v[116:119]
	s_waitcnt lgkmcnt(13)
	v_mfma_f32_16x16x32_bf16 v[120:123], v[124:127], v[12:15], v[204:207]
	s_waitcnt lgkmcnt(12)
	v_mfma_f32_16x16x32_bf16 v[204:207], v[128:131], v[16:19], v[120:123]
	s_waitcnt lgkmcnt(11)
	v_mfma_f32_16x16x32_bf16 v[120:123], v[132:135], v[4:7], 0
	s_waitcnt lgkmcnt(10)
	v_mfma_f32_16x16x32_bf16 v[120:123], v[136:139], v[8:11], v[120:123]
	v_mfma_f32_16x16x32_bf16 v[116:119], v[124:127], v[28:31], v[116:119]
	v_mfma_f32_16x16x32_bf16 v[124:127], v[132:135], v[20:23], 0
	s_waitcnt lgkmcnt(9)
	v_mfma_f32_16x16x32_bf16 v[120:123], v[140:143], v[12:15], v[120:123]
	v_mfma_f32_16x16x32_bf16 v[124:127], v[136:139], v[24:27], v[124:127]
	s_waitcnt lgkmcnt(8)
	v_mfma_f32_16x16x32_bf16 v[136:139], v[144:147], v[16:19], v[120:123]
	s_waitcnt lgkmcnt(7)
	v_mfma_f32_16x16x32_bf16 v[120:123], v[156:159], v[4:7], 0
	s_waitcnt lgkmcnt(6)
	v_mfma_f32_16x16x32_bf16 v[120:123], v[174:177], v[8:11], v[120:123]
	s_waitcnt lgkmcnt(5)
	v_mfma_f32_16x16x32_bf16 v[120:123], v[180:183], v[12:15], v[120:123]
	v_mfma_f32_16x16x32_bf16 v[124:127], v[140:143], v[28:31], v[124:127]
	s_waitcnt lgkmcnt(4)
	v_mfma_f32_16x16x32_bf16 v[140:143], v[184:187], v[16:19], v[120:123]
	s_waitcnt lgkmcnt(3)
	v_mfma_f32_16x16x32_bf16 v[120:123], v[188:191], v[4:7], 0
	v_mfma_f32_16x16x32_bf16 v[132:135], v[188:191], v[20:23], 0
	s_waitcnt lgkmcnt(2)
	v_mfma_f32_16x16x32_bf16 v[120:123], v[192:195], v[8:11], v[120:123]
	v_mfma_f32_16x16x32_bf16 v[132:135], v[192:195], v[24:27], v[132:135]
	v_mfma_f32_16x16x32_bf16 v[124:127], v[144:147], v[32:35], v[124:127]
	s_waitcnt lgkmcnt(1)
	v_mfma_f32_16x16x32_bf16 v[120:123], v[196:199], v[12:15], v[120:123]
	v_mfma_f32_16x16x32_bf16 v[144:147], v[196:199], v[28:31], v[132:135]
	s_waitcnt lgkmcnt(0)
	v_mfma_f32_16x16x32_bf16 v[132:135], v[200:203], v[16:19], v[120:123]
	v_mfma_f32_16x16x32_bf16 v[120:123], v[200:203], v[32:35], v[144:147]
	s_nop 4
	v_mul_f32_e32 v144, 0x3e0293ee, v204
	v_mul_f32_e32 v145, 0x3e0293ee, v205
	v_max3_f32 v144, v144, s82, v145
	v_mul_f32_e32 v145, 0x3e0293ee, v206
	v_mul_f32_e32 v146, 0x3e0293ee, v207
	v_max3_f32 v144, v144, v145, v146
	v_mul_f32_e32 v145, 0x3e0293ee, v136
	v_mul_f32_e32 v146, 0x3e0293ee, v137
	v_max3_f32 v144, v144, v145, v146
	v_mul_f32_e32 v145, 0x3e0293ee, v138
	v_mul_f32_e32 v146, 0x3e0293ee, v139
	v_max3_f32 v144, v144, v145, v146
	v_mul_f32_e32 v145, 0x3e0293ee, v140
	v_mul_f32_e32 v146, 0x3e0293ee, v141
	v_max3_f32 v144, v144, v145, v146
	v_mul_f32_e32 v145, 0x3e0293ee, v142
	v_mul_f32_e32 v146, 0x3e0293ee, v143
	v_max3_f32 v144, v144, v145, v146
	v_mul_f32_e32 v145, 0x3e0293ee, v132
	v_mul_f32_e32 v146, 0x3e0293ee, v133
	v_max3_f32 v144, v144, v145, v146
	v_mul_f32_e32 v145, 0x3e0293ee, v134
	v_mul_f32_e32 v146, 0x3e0293ee, v135
	v_max3_f32 v144, v144, v145, v146
	v_mov_b32_e32 v145, v144
	v_mfma_f32_16x16x32_bf16 v[116:119], v[128:131], v[32:35], v[116:119]
	s_waitcnt lgkmcnt(0)
	s_nop 1
	v_permlane16_swap_b32_e32 v145, v144
	v_max_f32_e32 v144, v144, v145
	v_mov_b32_e32 v145, v144
	v_mfma_f32_16x16x32_bf16 v[128:131], v[156:159], v[20:23], 0
	s_waitcnt lgkmcnt(0)
	s_nop 1
	v_permlane32_swap_b32_e32 v145, v144
	v_max3_f32 v170, v0, v144, v145
	v_fma_f32 v144, v204, s74, -v170
	v_exp_f32_e32 v173, v144
	v_fma_f32 v145, v205, s74, -v170
	v_mfma_f32_16x16x32_bf16 v[128:131], v[174:177], v[24:27], v[128:131]
	v_exp_f32_e32 v174, v145
	v_fma_f32 v145, v206, s74, -v170
	v_exp_f32_e32 v175, v145
	v_fma_f32 v145, v207, s74, -v170
	v_exp_f32_e32 v176, v145
	v_fma_f32 v136, v136, s74, -v170
	v_add_f32_e32 v144, 0, v173
	v_exp_f32_e32 v177, v136
	v_fma_f32 v137, v137, s74, -v170
	v_mfma_f32_16x16x32_bf16 v[128:131], v[180:183], v[28:31], v[128:131]
	v_add_f32_e32 v144, v174, v144
	v_exp_f32_e32 v180, v137
	v_fma_f32 v137, v138, s74, -v170
	v_add_f32_e32 v144, v175, v144
	v_exp_f32_e32 v181, v137
	v_fma_f32 v137, v139, s74, -v170
	v_add_f32_e32 v144, v176, v144
	v_exp_f32_e32 v183, v137
	v_fma_f32 v137, v140, s74, -v170
	v_add_f32_e32 v136, v177, v144
	v_exp_f32_e32 v182, v137
	v_fma_f32 v137, v141, s74, -v170
	v_mfma_f32_16x16x32_bf16 v[128:131], v[184:187], v[32:35], v[128:131]
	v_add_f32_e32 v136, v180, v136
	v_exp_f32_e32 v184, v137
	v_fma_f32 v137, v142, s74, -v170
	v_add_f32_e32 v136, v181, v136
	v_exp_f32_e32 v185, v137
	v_fma_f32 v137, v143, s74, -v170
	v_add_f32_e32 v136, v183, v136
	v_exp_f32_e32 v186, v137
	v_fma_f32 v132, v132, s74, -v170
	v_add_f32_e32 v136, v182, v136
	v_exp_f32_e32 v187, v132
	v_fma_f32 v133, v133, s74, -v170
	v_add_f32_e32 v136, v184, v136
	v_exp_f32_e32 v188, v133
	v_fma_f32 v133, v134, s74, -v170
	v_add_f32_e32 v136, v185, v136
	v_exp_f32_e32 v189, v133
	v_fma_f32 v133, v135, s74, -v170
	v_add_f32_e32 v136, v186, v136
	v_exp_f32_e32 v190, v133
	v_add_f32_e32 v132, v187, v136
	v_add_f32_e32 v132, v188, v132
	v_add_f32_e32 v132, v189, v132
	v_cmp_gt_f32_e32 vcc, v170, v0
	v_add_f32_e32 v156, v190, v132
	s_cbranch_vccz .LBB0_1458
	v_sub_f32_e32 v132, v0, v170
	v_exp_f32_e32 v144, v132
	v_mov_b32_e32 v159, v3
	v_fma_f32 v158, v2, v144, v156
	v_pk_mul_f32 v[134:135], v[102:103], v[144:145] op_sel_hi:[1,0]
	v_pk_mul_f32 v[132:133], v[100:101], v[144:145] op_sel_hi:[1,0]
	v_pk_mul_f32 v[138:139], v[106:107], v[144:145] op_sel_hi:[1,0]
	v_pk_mul_f32 v[136:137], v[104:105], v[144:145] op_sel_hi:[1,0]
	v_pk_mul_f32 v[142:143], v[110:111], v[144:145] op_sel_hi:[1,0]
	v_pk_mul_f32 v[140:141], v[108:109], v[144:145] op_sel_hi:[1,0]
	v_pk_mul_f32 v[146:147], v[114:115], v[144:145] op_sel_hi:[1,0]
	v_pk_mul_f32 v[144:145], v[112:113], v[144:145] op_sel_hi:[1,0]
	s_cbranch_execnz .LBB0_1451

.LBB0_1451:
	v_mul_f32_e32 v0, 0x3e0293ee, v116
	v_mul_f32_e32 v2, 0x3e0293ee, v117
	v_max3_f32 v0, v0, s82, v2
	v_mul_f32_e32 v2, 0x3e0293ee, v118
	v_mul_f32_e32 v3, 0x3e0293ee, v119
	v_max3_f32 v0, v0, v2, v3
	v_mul_f32_e32 v2, 0x3e0293ee, v124
	v_mul_f32_e32 v3, 0x3e0293ee, v125
	v_max3_f32 v0, v0, v2, v3
	v_mul_f32_e32 v2, 0x3e0293ee, v126
	v_mul_f32_e32 v3, 0x3e0293ee, v127
	v_max3_f32 v0, v0, v2, v3
	v_mul_f32_e32 v2, 0x3e0293ee, v128
	v_mul_f32_e32 v3, 0x3e0293ee, v129
	v_max3_f32 v0, v0, v2, v3
	v_mul_f32_e32 v2, 0x3e0293ee, v130
	v_mul_f32_e32 v3, 0x3e0293ee, v131
	v_max3_f32 v0, v0, v2, v3
	v_mul_f32_e32 v2, 0x3e0293ee, v120
	v_mul_f32_e32 v3, 0x3e0293ee, v121
	v_max3_f32 v0, v0, v2, v3
	v_mul_f32_e32 v2, 0x3e0293ee, v122
	v_mul_f32_e32 v3, 0x3e0293ee, v123
	v_max3_f32 v0, v0, v2, v3
	v_mov_b32_e32 v2, v0
	s_waitcnt lgkmcnt(0)
	s_nop 1
	v_permlane16_swap_b32_e32 v2, v0
	v_max_f32_e32 v0, v0, v2
	v_mov_b32_e32 v2, v0
	s_waitcnt lgkmcnt(0)
	s_nop 1
	v_permlane32_swap_b32_e32 v2, v0
	v_max3_f32 v171, v172, v0, v2
	v_fma_f32 v0, v116, s74, -v171
	v_exp_f32_e32 v0, v0
	v_fma_f32 v2, v117, s74, -v171
	v_exp_f32_e32 v2, v2
	v_fma_f32 v3, v118, s74, -v171
	v_exp_f32_e32 v3, v3
	v_fma_f32 v100, v119, s74, -v171
	v_exp_f32_e32 v116, v100
	v_fma_f32 v101, v124, s74, -v171
	v_add_f32_e32 v100, 0, v0
	v_exp_f32_e32 v117, v101
	v_fma_f32 v101, v125, s74, -v171
	v_add_f32_e32 v100, v2, v100
	v_exp_f32_e32 v119, v101
	v_fma_f32 v101, v126, s74, -v171
	v_add_f32_e32 v100, v3, v100
	v_exp_f32_e32 v125, v101
	v_fma_f32 v101, v127, s74, -v171
	v_add_f32_e32 v100, v116, v100
	v_exp_f32_e32 v127, v101
	v_fma_f32 v101, v128, s74, -v171
	v_add_f32_e32 v100, v117, v100
	v_exp_f32_e32 v118, v101
	v_fma_f32 v101, v129, s74, -v171
	v_add_f32_e32 v100, v119, v100
	v_exp_f32_e32 v124, v101
	v_fma_f32 v101, v130, s74, -v171
	v_add_f32_e32 v100, v125, v100
	v_exp_f32_e32 v126, v101
	v_fma_f32 v101, v131, s74, -v171
	v_add_f32_e32 v100, v127, v100
	v_exp_f32_e32 v128, v101
	v_fma_f32 v101, v120, s74, -v171
	v_add_f32_e32 v100, v118, v100
	v_exp_f32_e32 v120, v101
	v_fma_f32 v101, v121, s74, -v171
	v_add_f32_e32 v100, v124, v100
	v_exp_f32_e32 v121, v101
	v_fma_f32 v101, v122, s74, -v171
	v_add_f32_e32 v100, v126, v100
	v_exp_f32_e32 v122, v101
	v_fma_f32 v101, v123, s74, -v171
	v_add_f32_e32 v100, v128, v100
	v_exp_f32_e32 v123, v101
	v_add_f32_e32 v100, v120, v100
	v_add_f32_e32 v100, v121, v100
	v_add_f32_e32 v100, v122, v100
	v_cmp_gt_f32_e32 vcc, v171, v172
	v_add_f32_e32 v129, v123, v100
	s_cbranch_vccz .LBB0_1459
	v_sub_f32_e32 v100, v172, v171
	v_exp_f32_e32 v112, v100
	v_mov_b32_e32 v156, v158
	v_fma_f32 v157, v159, v112, v129
	v_pk_mul_f32 v[102:103], v[86:87], v[112:113] op_sel_hi:[1,0]
	v_pk_mul_f32 v[100:101], v[84:85], v[112:113] op_sel_hi:[1,0]
	v_pk_mul_f32 v[106:107], v[90:91], v[112:113] op_sel_hi:[1,0]
	v_pk_mul_f32 v[104:105], v[88:89], v[112:113] op_sel_hi:[1,0]
	v_pk_mul_f32 v[110:111], v[94:95], v[112:113] op_sel_hi:[1,0]
	v_pk_mul_f32 v[108:109], v[92:93], v[112:113] op_sel_hi:[1,0]
	v_pk_mul_f32 v[114:115], v[98:99], v[112:113] op_sel_hi:[1,0]
	v_pk_mul_f32 v[112:113], v[96:97], v[112:113] op_sel_hi:[1,0]
	s_cbranch_execnz .LBB0_1454
